# v18: LN epilogue gain/bias of all 4 column groups loaded up front (no store drain before each group)
# baseline (speedup 1.0000x reference)
.LBB0_85:
	s_or_b64 exec, exec, s[6:7]
	v_readlane_b32 s4, v253, 9
	s_add_i32 s4, s4, -6
	v_readlane_b32 s36, v254, 35
	v_readlane_b32 s5, v253, 10
	s_cmp_lt_u32 s4, 5
	v_readlane_b32 s50, v254, 49
	v_readlane_b32 s51, v254, 50
	v_readlane_b32 s6, v255, 7
	s_cselect_b32 s5, s51, s1
	s_cselect_b32 s4, s50, s0
	v_readlane_b32 s7, v255, 8
	s_lshl_b32 s6, s6, 11
	s_ashr_i32 s7, s6, 31
	v_readlane_b32 s46, v254, 45
	s_lshl_b64 s[6:7], s[6:7], 2
	v_readlane_b32 s47, v254, 46
	s_add_u32 s8, s46, s6
	v_readlane_b32 s48, v254, 47
	s_addc_u32 s9, s47, s7
	v_readlane_b32 s49, v254, 48
	s_add_u32 s6, s48, s6
	v_mov_b32_e32 v139, v129
	s_addc_u32 s7, s49, s7
	v_lshlrev_b64 v[134:135], 2, v[138:139]
	v_lshl_add_u64 v[140:141], s[8:9], 0, v[134:135]
	v_lshl_add_u64 v[142:143], s[6:7], 0, v[134:135]
	s_waitcnt lgkmcnt(0)
	s_barrier
	global_load_dwordx4 v[130:133], v[140:141], off
	global_load_dwordx4 v[134:137], v[142:143], off
	global_load_dwordx4 v[196:199], v[140:141], off offset:64
	global_load_dwordx4 v[200:203], v[142:143], off offset:64
	global_load_dwordx4 v[204:207], v[140:141], off offset:512
	global_load_dwordx4 v[208:211], v[142:143], off offset:512
	global_load_dwordx4 v[212:215], v[140:141], off offset:576
	global_load_dwordx4 v[160:163], v[142:143], off offset:576
	s_lshl_b32 s6, s24, 3
	s_add_i32 s6, s6, 0
	v_lshl_add_u32 v139, v144, 3, s6
	ds_read_b64 v[152:153], v139 offset:8192
	s_waitcnt lgkmcnt(0)
	v_cmp_eq_u32_e32 vcc, 0, v128
	v_lshl_add_u32 v128, v146, 11, v138
	v_mov_b32_e32 v147, 0x7fc00000
	v_lshl_add_u64 v[156:157], v[128:129], 2, s[4:5]
	v_sub_f32_e32 v93, v93, v152
	v_sub_f32_e32 v92, v92, v152
	v_sub_f32_e32 v95, v95, v152
	v_sub_f32_e32 v94, v94, v152
	v_pk_mul_f32 v[94:95], v[152:153], v[94:95] op_sel:[1,0]
	v_pk_mul_f32 v[92:93], v[152:153], v[92:93] op_sel:[1,0]
	v_readlane_b32 s6, v255, 9
	v_mov_b32_e32 v145, v129
	v_readlane_b32 s7, v255, 10
	v_add_u32_e32 v144, 0x8000, v128
	v_mov_b32_e32 v149, v129
	v_lshl_add_u64 v[152:153], v[128:129], 1, s[6:7]
	v_add_u32_e32 v148, 0x10000, v128
	v_mov_b32_e32 v151, v129
	v_add_u32_e32 v150, 0x18000, v128
	v_mov_b32_e32 v155, v129
	v_add_u32_e32 v154, 0x40000, v128
	v_readlane_b32 s37, v254, 36
	v_readlane_b32 s38, v254, 37
	v_readlane_b32 s39, v254, 38
	v_readlane_b32 s40, v254, 39
	v_readlane_b32 s41, v254, 40
	v_readlane_b32 s42, v254, 41
	v_readlane_b32 s43, v254, 42
	v_readlane_b32 s44, v254, 43
	v_readlane_b32 s45, v254, 44
	s_waitcnt vmcnt(0)
	v_pk_fma_f32 v[92:93], v[130:131], v[92:93], v[134:135]
	v_pk_fma_f32 v[94:95], v[132:133], v[94:95], v[136:137]
	v_cndmask_b32_e32 v93, v147, v93, vcc
	v_cndmask_b32_e32 v95, v147, v95, vcc
	v_cndmask_b32_e32 v94, v147, v94, vcc
	v_cndmask_b32_e32 v92, v147, v92, vcc
	global_store_dwordx4 v[156:157], v[92:95], off nt
	v_lshl_add_u64 v[156:157], v[144:145], 2, s[4:5]
	s_nop 0
	v_cvt_pk_bf16_f32 v92, v92, v93
	v_cvt_pk_bf16_f32 v93, v94, v95
	ds_read_b64 v[94:95], v139 offset:8320
	global_store_dwordx2 v[152:153], v[92:93], off
	v_lshl_add_u64 v[92:93], v[144:145], 1, s[6:7]
	s_waitcnt lgkmcnt(0)
	v_sub_f32_e32 v89, v89, v94
	v_sub_f32_e32 v88, v88, v94
	v_sub_f32_e32 v91, v91, v94
	v_sub_f32_e32 v90, v90, v94
	v_pk_mul_f32 v[90:91], v[94:95], v[90:91] op_sel:[1,0]
	v_pk_mul_f32 v[88:89], v[94:95], v[88:89] op_sel:[1,0]
	v_pk_fma_f32 v[90:91], v[132:133], v[90:91], v[136:137]
	v_pk_fma_f32 v[88:89], v[130:131], v[88:89], v[134:135]
	v_cndmask_b32_e32 v91, v147, v91, vcc
	v_cndmask_b32_e32 v90, v147, v90, vcc
	v_cndmask_b32_e32 v89, v147, v89, vcc
	v_cndmask_b32_e32 v88, v147, v88, vcc
	global_store_dwordx4 v[156:157], v[88:91], off nt
	v_lshl_add_u64 v[94:95], v[148:149], 2, s[4:5]
	s_nop 0
	v_cvt_pk_bf16_f32 v88, v88, v89
	v_cvt_pk_bf16_f32 v89, v90, v91
	ds_read_b64 v[90:91], v139 offset:8448
	global_store_dwordx2 v[92:93], v[88:89], off
	v_lshl_add_u64 v[88:89], v[148:149], 1, s[6:7]
	s_waitcnt lgkmcnt(0)
	v_sub_f32_e32 v85, v85, v90
	v_sub_f32_e32 v84, v84, v90
	v_sub_f32_e32 v87, v87, v90
	v_sub_f32_e32 v86, v86, v90
	v_pk_mul_f32 v[86:87], v[90:91], v[86:87] op_sel:[1,0]
	v_pk_mul_f32 v[84:85], v[90:91], v[84:85] op_sel:[1,0]
	v_pk_fma_f32 v[86:87], v[132:133], v[86:87], v[136:137]
	v_pk_fma_f32 v[84:85], v[130:131], v[84:85], v[134:135]
	v_cndmask_b32_e32 v87, v147, v87, vcc
	v_cndmask_b32_e32 v86, v147, v86, vcc
	v_cndmask_b32_e32 v85, v147, v85, vcc
	v_cndmask_b32_e32 v84, v147, v84, vcc
	global_store_dwordx4 v[94:95], v[84:87], off nt
	v_lshl_add_u64 v[90:91], v[150:151], 2, s[4:5]
	s_nop 0
	v_cvt_pk_bf16_f32 v84, v84, v85
	v_cvt_pk_bf16_f32 v85, v86, v87
	ds_read_b64 v[86:87], v139 offset:8576
	global_store_dwordx2 v[88:89], v[84:85], off
	v_lshl_add_u64 v[84:85], v[150:151], 1, s[6:7]
	s_waitcnt lgkmcnt(0)
	v_sub_f32_e32 v81, v81, v86
	v_sub_f32_e32 v80, v80, v86
	v_sub_f32_e32 v83, v83, v86
	v_sub_f32_e32 v82, v82, v86
	v_pk_mul_f32 v[82:83], v[86:87], v[82:83] op_sel:[1,0]
	v_pk_mul_f32 v[80:81], v[86:87], v[80:81] op_sel:[1,0]
	v_pk_fma_f32 v[82:83], v[132:133], v[82:83], v[136:137]
	v_pk_fma_f32 v[80:81], v[130:131], v[80:81], v[134:135]
	v_cndmask_b32_e32 v83, v147, v83, vcc
	v_cndmask_b32_e32 v82, v147, v82, vcc
	v_cndmask_b32_e32 v81, v147, v81, vcc
	v_cndmask_b32_e32 v80, v147, v80, vcc
	global_store_dwordx4 v[90:91], v[80:83], off nt
	v_lshl_add_u64 v[86:87], v[154:155], 2, s[4:5]
	s_nop 0
	v_cvt_pk_bf16_f32 v80, v80, v81
	v_cvt_pk_bf16_f32 v81, v82, v83
	ds_read_b64 v[82:83], v139 offset:9216
	global_store_dwordx2 v[84:85], v[80:81], off
	s_waitcnt lgkmcnt(0)
	v_sub_f32_e32 v81, v125, v82
	v_sub_f32_e32 v80, v124, v82
	v_sub_f32_e32 v85, v127, v82
	v_sub_f32_e32 v84, v126, v82
	v_pk_mul_f32 v[84:85], v[82:83], v[84:85] op_sel:[1,0]
	v_pk_mul_f32 v[80:81], v[82:83], v[80:81] op_sel:[1,0]
	v_pk_fma_f32 v[82:83], v[132:133], v[84:85], v[136:137]
	v_pk_fma_f32 v[80:81], v[130:131], v[80:81], v[134:135]
	v_cndmask_b32_e32 v83, v147, v83, vcc
	v_cndmask_b32_e32 v82, v147, v82, vcc
	v_cndmask_b32_e32 v81, v147, v81, vcc
	v_cndmask_b32_e32 v80, v147, v80, vcc
	global_store_dwordx4 v[86:87], v[80:83], off nt
	v_lshl_add_u64 v[86:87], v[154:155], 1, s[6:7]
	v_add_u32_e32 v84, 0x48000, v128
	v_cvt_pk_bf16_f32 v80, v80, v81
	v_cvt_pk_bf16_f32 v81, v82, v83
	ds_read_b64 v[82:83], v139 offset:9344
	global_store_dwordx2 v[86:87], v[80:81], off
	v_mov_b32_e32 v85, v129
	s_waitcnt lgkmcnt(0)
	v_sub_f32_e32 v81, v121, v82
	v_sub_f32_e32 v80, v120, v82
	v_sub_f32_e32 v87, v123, v82
	v_sub_f32_e32 v86, v122, v82
	v_pk_mul_f32 v[86:87], v[82:83], v[86:87] op_sel:[1,0]
	v_pk_mul_f32 v[80:81], v[82:83], v[80:81] op_sel:[1,0]
	v_pk_fma_f32 v[82:83], v[132:133], v[86:87], v[136:137]
	v_pk_fma_f32 v[80:81], v[130:131], v[80:81], v[134:135]
	v_cndmask_b32_e32 v83, v147, v83, vcc
	v_cndmask_b32_e32 v82, v147, v82, vcc
	v_cndmask_b32_e32 v81, v147, v81, vcc
	v_cndmask_b32_e32 v80, v147, v80, vcc
	v_lshl_add_u64 v[86:87], v[84:85], 2, s[4:5]
	global_store_dwordx4 v[86:87], v[80:83], off nt
	v_lshl_add_u64 v[84:85], v[84:85], 1, s[6:7]
	s_nop 0
	v_cvt_pk_bf16_f32 v80, v80, v81
	v_cvt_pk_bf16_f32 v81, v82, v83
	ds_read_b64 v[82:83], v139 offset:9472
	global_store_dwordx2 v[84:85], v[80:81], off
	v_add_u32_e32 v84, 0x50000, v128
	v_mov_b32_e32 v85, v129
	v_add_u32_e32 v128, 0x58000, v128
	s_waitcnt lgkmcnt(0)
	v_sub_f32_e32 v81, v117, v82
	v_sub_f32_e32 v80, v116, v82
	v_sub_f32_e32 v87, v119, v82
	v_sub_f32_e32 v86, v118, v82
	v_pk_mul_f32 v[86:87], v[82:83], v[86:87] op_sel:[1,0]
	v_pk_mul_f32 v[80:81], v[82:83], v[80:81] op_sel:[1,0]
	v_pk_fma_f32 v[82:83], v[132:133], v[86:87], v[136:137]
	v_pk_fma_f32 v[80:81], v[130:131], v[80:81], v[134:135]
	v_cndmask_b32_e32 v83, v147, v83, vcc
	v_cndmask_b32_e32 v82, v147, v82, vcc
	v_cndmask_b32_e32 v81, v147, v81, vcc
	v_cndmask_b32_e32 v80, v147, v80, vcc
	v_lshl_add_u64 v[86:87], v[84:85], 2, s[4:5]
	global_store_dwordx4 v[86:87], v[80:83], off nt
	v_lshl_add_u64 v[84:85], v[84:85], 1, s[6:7]
	s_nop 0
	v_cvt_pk_bf16_f32 v80, v80, v81
	v_cvt_pk_bf16_f32 v81, v82, v83
	ds_read_b64 v[82:83], v139 offset:9600
	global_store_dwordx2 v[84:85], v[80:81], off
	s_waitcnt lgkmcnt(0)
	v_sub_f32_e32 v81, v113, v82
	v_sub_f32_e32 v80, v112, v82
	v_sub_f32_e32 v85, v115, v82
	v_sub_f32_e32 v84, v114, v82
	v_pk_mul_f32 v[84:85], v[82:83], v[84:85] op_sel:[1,0]
	v_pk_mul_f32 v[80:81], v[82:83], v[80:81] op_sel:[1,0]
	v_pk_fma_f32 v[82:83], v[132:133], v[84:85], v[136:137]
	v_pk_fma_f32 v[80:81], v[130:131], v[80:81], v[134:135]
	v_cndmask_b32_e32 v83, v147, v83, vcc
	v_cndmask_b32_e32 v82, v147, v82, vcc
	v_cndmask_b32_e32 v81, v147, v81, vcc
	v_cndmask_b32_e32 v80, v147, v80, vcc
	v_lshl_add_u64 v[84:85], v[128:129], 2, s[4:5]
	global_store_dwordx4 v[84:85], v[80:83], off nt
	s_nop 1
	v_cvt_pk_bf16_f32 v80, v80, v81
	v_cvt_pk_bf16_f32 v81, v82, v83
	v_lshl_add_u64 v[82:83], v[128:129], 1, s[6:7]
	global_store_dwordx2 v[82:83], v[80:81], off
	ds_read_b64 v[88:89], v139 offset:8192
	v_lshl_add_u32 v92, v146, 11, v138
	v_add_u32_e32 v128, 16, v92
	v_lshl_add_u64 v[90:91], v[128:129], 2, s[4:5]
	s_waitcnt lgkmcnt(0)
	v_sub_f32_e32 v61, v61, v88
	v_sub_f32_e32 v60, v60, v88
	v_sub_f32_e32 v63, v63, v88
	v_sub_f32_e32 v62, v62, v88
	v_pk_mul_f32 v[62:63], v[88:89], v[62:63] op_sel:[1,0]
	v_pk_mul_f32 v[60:61], v[88:89], v[60:61] op_sel:[1,0]
	v_lshl_add_u64 v[88:89], v[128:129], 1, s[6:7]
	v_add_u32_e32 v128, 0x8010, v92
	v_pk_fma_f32 v[60:61], v[196:197], v[60:61], v[200:201]
	v_pk_fma_f32 v[62:63], v[198:199], v[62:63], v[202:203]
	v_cndmask_b32_e32 v61, v147, v61, vcc
	v_cndmask_b32_e32 v63, v147, v63, vcc
	v_cndmask_b32_e32 v62, v147, v62, vcc
	v_cndmask_b32_e32 v60, v147, v60, vcc
	global_store_dwordx4 v[90:91], v[60:63], off nt
	v_lshl_add_u64 v[90:91], v[128:129], 2, s[4:5]
	s_nop 0
	v_cvt_pk_bf16_f32 v60, v60, v61
	v_cvt_pk_bf16_f32 v61, v62, v63
	ds_read_b64 v[62:63], v139 offset:8320
	global_store_dwordx2 v[88:89], v[60:61], off
	v_lshl_add_u64 v[60:61], v[128:129], 1, s[6:7]
	v_add_u32_e32 v128, 0x10010, v92
	s_waitcnt lgkmcnt(0)
	v_sub_f32_e32 v57, v57, v62
	v_sub_f32_e32 v56, v56, v62
	v_sub_f32_e32 v59, v59, v62
	v_sub_f32_e32 v58, v58, v62
	v_pk_mul_f32 v[58:59], v[62:63], v[58:59] op_sel:[1,0]
	v_pk_mul_f32 v[56:57], v[62:63], v[56:57] op_sel:[1,0]
	v_pk_fma_f32 v[58:59], v[198:199], v[58:59], v[202:203]
	v_pk_fma_f32 v[56:57], v[196:197], v[56:57], v[200:201]
	v_cndmask_b32_e32 v59, v147, v59, vcc
	v_cndmask_b32_e32 v58, v147, v58, vcc
	v_cndmask_b32_e32 v57, v147, v57, vcc
	v_cndmask_b32_e32 v56, v147, v56, vcc
	global_store_dwordx4 v[90:91], v[56:59], off nt
	v_lshl_add_u64 v[62:63], v[128:129], 2, s[4:5]
	s_nop 0
	v_cvt_pk_bf16_f32 v56, v56, v57
	v_cvt_pk_bf16_f32 v57, v58, v59
	ds_read_b64 v[58:59], v139 offset:8448
	global_store_dwordx2 v[60:61], v[56:57], off
	v_lshl_add_u64 v[56:57], v[128:129], 1, s[6:7]
	v_add_u32_e32 v128, 0x18010, v92
	s_waitcnt lgkmcnt(0)
	v_sub_f32_e32 v53, v53, v58
	v_sub_f32_e32 v52, v52, v58
	v_sub_f32_e32 v55, v55, v58
	v_sub_f32_e32 v54, v54, v58
	v_pk_mul_f32 v[54:55], v[58:59], v[54:55] op_sel:[1,0]
	v_pk_mul_f32 v[52:53], v[58:59], v[52:53] op_sel:[1,0]
	v_pk_fma_f32 v[54:55], v[198:199], v[54:55], v[202:203]
	v_pk_fma_f32 v[52:53], v[196:197], v[52:53], v[200:201]
	v_cndmask_b32_e32 v55, v147, v55, vcc
	v_cndmask_b32_e32 v54, v147, v54, vcc
	v_cndmask_b32_e32 v53, v147, v53, vcc
	v_cndmask_b32_e32 v52, v147, v52, vcc
	global_store_dwordx4 v[62:63], v[52:55], off nt
	s_nop 1
	v_cvt_pk_bf16_f32 v52, v52, v53
	v_cvt_pk_bf16_f32 v53, v54, v55
	ds_read_b64 v[54:55], v139 offset:8576
	global_store_dwordx2 v[56:57], v[52:53], off
	v_lshl_add_u64 v[52:53], v[128:129], 2, s[4:5]
	s_waitcnt lgkmcnt(0)
	v_sub_f32_e32 v49, v49, v54
	v_sub_f32_e32 v48, v48, v54
	v_sub_f32_e32 v51, v51, v54
	v_sub_f32_e32 v50, v50, v54
	v_pk_mul_f32 v[50:51], v[54:55], v[50:51] op_sel:[1,0]
	v_pk_mul_f32 v[48:49], v[54:55], v[48:49] op_sel:[1,0]
	v_pk_fma_f32 v[50:51], v[198:199], v[50:51], v[202:203]
	v_pk_fma_f32 v[48:49], v[196:197], v[48:49], v[200:201]
	v_cndmask_b32_e32 v51, v147, v51, vcc
	v_cndmask_b32_e32 v50, v147, v50, vcc
	v_cndmask_b32_e32 v49, v147, v49, vcc
	v_cndmask_b32_e32 v48, v147, v48, vcc
	global_store_dwordx4 v[52:53], v[48:51], off nt
	v_lshl_add_u64 v[52:53], v[128:129], 1, s[6:7]
	v_add_u32_e32 v128, 0x40010, v92
	v_cvt_pk_bf16_f32 v48, v48, v49
	v_cvt_pk_bf16_f32 v49, v50, v51
	ds_read_b64 v[50:51], v139 offset:9216
	global_store_dwordx2 v[52:53], v[48:49], off
	s_waitcnt lgkmcnt(0)
	v_sub_f32_e32 v49, v109, v50
	v_sub_f32_e32 v48, v108, v50
	v_sub_f32_e32 v53, v111, v50
	v_sub_f32_e32 v52, v110, v50
	v_pk_mul_f32 v[52:53], v[50:51], v[52:53] op_sel:[1,0]
	v_pk_mul_f32 v[48:49], v[50:51], v[48:49] op_sel:[1,0]
	v_pk_fma_f32 v[50:51], v[198:199], v[52:53], v[202:203]
	v_pk_fma_f32 v[48:49], v[196:197], v[48:49], v[200:201]
	v_cndmask_b32_e32 v51, v147, v51, vcc
	v_cndmask_b32_e32 v50, v147, v50, vcc
	v_cndmask_b32_e32 v49, v147, v49, vcc
	v_cndmask_b32_e32 v48, v147, v48, vcc
	v_lshl_add_u64 v[52:53], v[128:129], 2, s[4:5]
	global_store_dwordx4 v[52:53], v[48:51], off nt
	v_lshl_add_u64 v[52:53], v[128:129], 1, s[6:7]
	v_add_u32_e32 v128, 0x48010, v92
	v_cvt_pk_bf16_f32 v48, v48, v49
	v_cvt_pk_bf16_f32 v49, v50, v51
	ds_read_b64 v[50:51], v139 offset:9344
	global_store_dwordx2 v[52:53], v[48:49], off
	s_waitcnt lgkmcnt(0)
	v_sub_f32_e32 v49, v105, v50
	v_sub_f32_e32 v48, v104, v50
	v_sub_f32_e32 v53, v107, v50
	v_sub_f32_e32 v52, v106, v50
	v_pk_mul_f32 v[52:53], v[50:51], v[52:53] op_sel:[1,0]
	v_pk_mul_f32 v[48:49], v[50:51], v[48:49] op_sel:[1,0]
	v_pk_fma_f32 v[50:51], v[198:199], v[52:53], v[202:203]
	v_pk_fma_f32 v[48:49], v[196:197], v[48:49], v[200:201]
	v_cndmask_b32_e32 v51, v147, v51, vcc
	v_cndmask_b32_e32 v50, v147, v50, vcc
	v_cndmask_b32_e32 v49, v147, v49, vcc
	v_cndmask_b32_e32 v48, v147, v48, vcc
	v_lshl_add_u64 v[52:53], v[128:129], 2, s[4:5]
	global_store_dwordx4 v[52:53], v[48:51], off nt
	v_lshl_add_u64 v[52:53], v[128:129], 1, s[6:7]
	v_add_u32_e32 v128, 0x50010, v92
	v_cvt_pk_bf16_f32 v48, v48, v49
	v_cvt_pk_bf16_f32 v49, v50, v51
	ds_read_b64 v[50:51], v139 offset:9472
	global_store_dwordx2 v[52:53], v[48:49], off
	s_waitcnt lgkmcnt(0)
	v_sub_f32_e32 v49, v101, v50
	v_sub_f32_e32 v48, v100, v50
	v_sub_f32_e32 v53, v103, v50
	v_sub_f32_e32 v52, v102, v50
	v_pk_mul_f32 v[52:53], v[50:51], v[52:53] op_sel:[1,0]
	v_pk_mul_f32 v[48:49], v[50:51], v[48:49] op_sel:[1,0]
	v_pk_fma_f32 v[50:51], v[198:199], v[52:53], v[202:203]
	v_pk_fma_f32 v[48:49], v[196:197], v[48:49], v[200:201]
	v_cndmask_b32_e32 v51, v147, v51, vcc
	v_cndmask_b32_e32 v50, v147, v50, vcc
	v_cndmask_b32_e32 v49, v147, v49, vcc
	v_cndmask_b32_e32 v48, v147, v48, vcc
	v_lshl_add_u64 v[52:53], v[128:129], 2, s[4:5]
	global_store_dwordx4 v[52:53], v[48:51], off nt
	v_lshl_add_u64 v[52:53], v[128:129], 1, s[6:7]
	v_add_u32_e32 v128, 0x58010, v92
	v_cvt_pk_bf16_f32 v48, v48, v49
	v_cvt_pk_bf16_f32 v49, v50, v51
	ds_read_b64 v[50:51], v139 offset:9600
	global_store_dwordx2 v[52:53], v[48:49], off
	s_waitcnt lgkmcnt(0)
	v_sub_f32_e32 v49, v97, v50
	v_sub_f32_e32 v48, v96, v50
	v_sub_f32_e32 v53, v99, v50
	v_sub_f32_e32 v52, v98, v50
	v_pk_mul_f32 v[52:53], v[50:51], v[52:53] op_sel:[1,0]
	v_pk_mul_f32 v[48:49], v[50:51], v[48:49] op_sel:[1,0]
	v_pk_fma_f32 v[50:51], v[198:199], v[52:53], v[202:203]
	v_pk_fma_f32 v[48:49], v[196:197], v[48:49], v[200:201]
	v_cndmask_b32_e32 v51, v147, v51, vcc
	v_cndmask_b32_e32 v50, v147, v50, vcc
	v_cndmask_b32_e32 v49, v147, v49, vcc
	v_cndmask_b32_e32 v48, v147, v48, vcc
	v_lshl_add_u64 v[52:53], v[128:129], 2, s[4:5]
	global_store_dwordx4 v[52:53], v[48:51], off nt
	s_nop 1
	v_cvt_pk_bf16_f32 v48, v48, v49
	v_cvt_pk_bf16_f32 v49, v50, v51
	v_lshl_add_u64 v[50:51], v[128:129], 1, s[6:7]
	global_store_dwordx2 v[50:51], v[48:49], off
	ds_read_b64 v[56:57], v139 offset:8192
	v_lshl_add_u32 v60, v146, 11, v138
	v_add_u32_e32 v128, 0x80, v60
	v_lshl_add_u64 v[58:59], v[128:129], 2, s[4:5]
	s_waitcnt lgkmcnt(0)
	v_sub_f32_e32 v29, v29, v56
	v_sub_f32_e32 v28, v28, v56
	v_sub_f32_e32 v31, v31, v56
	v_sub_f32_e32 v30, v30, v56
	v_pk_mul_f32 v[30:31], v[56:57], v[30:31] op_sel:[1,0]
	v_pk_mul_f32 v[28:29], v[56:57], v[28:29] op_sel:[1,0]
	v_lshl_add_u64 v[56:57], v[128:129], 1, s[6:7]
	v_add_u32_e32 v128, 0x8080, v60
	v_pk_fma_f32 v[28:29], v[204:205], v[28:29], v[208:209]
	v_pk_fma_f32 v[30:31], v[206:207], v[30:31], v[210:211]
	v_cndmask_b32_e32 v29, v147, v29, vcc
	v_cndmask_b32_e32 v31, v147, v31, vcc
	v_cndmask_b32_e32 v30, v147, v30, vcc
	v_cndmask_b32_e32 v28, v147, v28, vcc
	global_store_dwordx4 v[58:59], v[28:31], off nt
	v_lshl_add_u64 v[58:59], v[128:129], 2, s[4:5]
	s_nop 0
	v_cvt_pk_bf16_f32 v28, v28, v29
	v_cvt_pk_bf16_f32 v29, v30, v31
	ds_read_b64 v[30:31], v139 offset:8320
	global_store_dwordx2 v[56:57], v[28:29], off
	v_lshl_add_u64 v[28:29], v[128:129], 1, s[6:7]
	v_add_u32_e32 v128, 0x10080, v60
	s_waitcnt lgkmcnt(0)
	v_sub_f32_e32 v25, v25, v30
	v_sub_f32_e32 v24, v24, v30
	v_sub_f32_e32 v27, v27, v30
	v_sub_f32_e32 v26, v26, v30
	v_pk_mul_f32 v[26:27], v[30:31], v[26:27] op_sel:[1,0]
	v_pk_mul_f32 v[24:25], v[30:31], v[24:25] op_sel:[1,0]
	v_pk_fma_f32 v[26:27], v[206:207], v[26:27], v[210:211]
	v_pk_fma_f32 v[24:25], v[204:205], v[24:25], v[208:209]
	v_cndmask_b32_e32 v27, v147, v27, vcc
	v_cndmask_b32_e32 v26, v147, v26, vcc
	v_cndmask_b32_e32 v25, v147, v25, vcc
	v_cndmask_b32_e32 v24, v147, v24, vcc
	global_store_dwordx4 v[58:59], v[24:27], off nt
	s_nop 1
	v_cvt_pk_bf16_f32 v24, v24, v25
	v_cvt_pk_bf16_f32 v25, v26, v27
	ds_read_b64 v[26:27], v139 offset:8448
	global_store_dwordx2 v[28:29], v[24:25], off
	v_lshl_add_u64 v[24:25], v[128:129], 2, s[4:5]
	s_waitcnt lgkmcnt(0)
	v_sub_f32_e32 v21, v21, v26
	v_sub_f32_e32 v20, v20, v26
	v_sub_f32_e32 v23, v23, v26
	v_sub_f32_e32 v22, v22, v26
	v_pk_mul_f32 v[22:23], v[26:27], v[22:23] op_sel:[1,0]
	v_pk_mul_f32 v[20:21], v[26:27], v[20:21] op_sel:[1,0]
	v_pk_fma_f32 v[22:23], v[206:207], v[22:23], v[210:211]
	v_pk_fma_f32 v[20:21], v[204:205], v[20:21], v[208:209]
	v_cndmask_b32_e32 v23, v147, v23, vcc
	v_cndmask_b32_e32 v22, v147, v22, vcc
	v_cndmask_b32_e32 v21, v147, v21, vcc
	v_cndmask_b32_e32 v20, v147, v20, vcc
	global_store_dwordx4 v[24:25], v[20:23], off nt
	v_lshl_add_u64 v[24:25], v[128:129], 1, s[6:7]
	v_add_u32_e32 v128, 0x18080, v60
	v_cvt_pk_bf16_f32 v20, v20, v21
	v_cvt_pk_bf16_f32 v21, v22, v23
	ds_read_b64 v[22:23], v139 offset:8576
	global_store_dwordx2 v[24:25], v[20:21], off
	v_lshl_add_u64 v[20:21], v[128:129], 2, s[4:5]
	s_waitcnt lgkmcnt(0)
	v_sub_f32_e32 v17, v17, v22
	v_sub_f32_e32 v16, v16, v22
	v_sub_f32_e32 v19, v19, v22
	v_sub_f32_e32 v18, v18, v22
	v_pk_mul_f32 v[18:19], v[22:23], v[18:19] op_sel:[1,0]
	v_pk_mul_f32 v[16:17], v[22:23], v[16:17] op_sel:[1,0]
	v_pk_fma_f32 v[18:19], v[206:207], v[18:19], v[210:211]
	v_pk_fma_f32 v[16:17], v[204:205], v[16:17], v[208:209]
	v_cndmask_b32_e32 v19, v147, v19, vcc
	v_cndmask_b32_e32 v18, v147, v18, vcc
	v_cndmask_b32_e32 v17, v147, v17, vcc
	v_cndmask_b32_e32 v16, v147, v16, vcc
	global_store_dwordx4 v[20:21], v[16:19], off nt
	v_lshl_add_u64 v[20:21], v[128:129], 1, s[6:7]
	v_add_u32_e32 v128, 0x40080, v60
	v_cvt_pk_bf16_f32 v16, v16, v17
	v_cvt_pk_bf16_f32 v17, v18, v19
	ds_read_b64 v[18:19], v139 offset:9216
	global_store_dwordx2 v[20:21], v[16:17], off
	s_waitcnt lgkmcnt(0)
	v_sub_f32_e32 v17, v77, v18
	v_sub_f32_e32 v16, v76, v18
	v_sub_f32_e32 v21, v79, v18
	v_sub_f32_e32 v20, v78, v18
	v_pk_mul_f32 v[20:21], v[18:19], v[20:21] op_sel:[1,0]
	v_pk_mul_f32 v[16:17], v[18:19], v[16:17] op_sel:[1,0]
	v_pk_fma_f32 v[18:19], v[206:207], v[20:21], v[210:211]
	v_pk_fma_f32 v[16:17], v[204:205], v[16:17], v[208:209]
	v_cndmask_b32_e32 v19, v147, v19, vcc
	v_cndmask_b32_e32 v18, v147, v18, vcc
	v_cndmask_b32_e32 v17, v147, v17, vcc
	v_cndmask_b32_e32 v16, v147, v16, vcc
	v_lshl_add_u64 v[20:21], v[128:129], 2, s[4:5]
	global_store_dwordx4 v[20:21], v[16:19], off nt
	v_lshl_add_u64 v[20:21], v[128:129], 1, s[6:7]
	v_add_u32_e32 v128, 0x48080, v60
	v_cvt_pk_bf16_f32 v16, v16, v17
	v_cvt_pk_bf16_f32 v17, v18, v19
	ds_read_b64 v[18:19], v139 offset:9344
	global_store_dwordx2 v[20:21], v[16:17], off
	s_waitcnt lgkmcnt(0)
	v_sub_f32_e32 v17, v73, v18
	v_sub_f32_e32 v16, v72, v18
	v_sub_f32_e32 v21, v75, v18
	v_sub_f32_e32 v20, v74, v18
	v_pk_mul_f32 v[20:21], v[18:19], v[20:21] op_sel:[1,0]
	v_pk_mul_f32 v[16:17], v[18:19], v[16:17] op_sel:[1,0]
	v_pk_fma_f32 v[18:19], v[206:207], v[20:21], v[210:211]
	v_pk_fma_f32 v[16:17], v[204:205], v[16:17], v[208:209]
	v_cndmask_b32_e32 v19, v147, v19, vcc
	v_cndmask_b32_e32 v18, v147, v18, vcc
	v_cndmask_b32_e32 v17, v147, v17, vcc
	v_cndmask_b32_e32 v16, v147, v16, vcc
	v_lshl_add_u64 v[20:21], v[128:129], 2, s[4:5]
	global_store_dwordx4 v[20:21], v[16:19], off nt
	v_lshl_add_u64 v[20:21], v[128:129], 1, s[6:7]
	v_add_u32_e32 v128, 0x50080, v60
	v_cvt_pk_bf16_f32 v16, v16, v17
	v_cvt_pk_bf16_f32 v17, v18, v19
	ds_read_b64 v[18:19], v139 offset:9472
	global_store_dwordx2 v[20:21], v[16:17], off
	s_waitcnt lgkmcnt(0)
	v_sub_f32_e32 v17, v69, v18
	v_sub_f32_e32 v16, v68, v18
	v_sub_f32_e32 v21, v71, v18
	v_sub_f32_e32 v20, v70, v18
	v_pk_mul_f32 v[20:21], v[18:19], v[20:21] op_sel:[1,0]
	v_pk_mul_f32 v[16:17], v[18:19], v[16:17] op_sel:[1,0]
	v_pk_fma_f32 v[18:19], v[206:207], v[20:21], v[210:211]
	v_pk_fma_f32 v[16:17], v[204:205], v[16:17], v[208:209]
	v_cndmask_b32_e32 v19, v147, v19, vcc
	v_cndmask_b32_e32 v18, v147, v18, vcc
	v_cndmask_b32_e32 v17, v147, v17, vcc
	v_cndmask_b32_e32 v16, v147, v16, vcc
	v_lshl_add_u64 v[20:21], v[128:129], 2, s[4:5]
	global_store_dwordx4 v[20:21], v[16:19], off nt
	v_lshl_add_u64 v[20:21], v[128:129], 1, s[6:7]
	v_add_u32_e32 v128, 0x58080, v60
	v_cvt_pk_bf16_f32 v16, v16, v17
	v_cvt_pk_bf16_f32 v17, v18, v19
	ds_read_b64 v[18:19], v139 offset:9600
	global_store_dwordx2 v[20:21], v[16:17], off
	s_waitcnt lgkmcnt(0)
	v_sub_f32_e32 v17, v65, v18
	v_sub_f32_e32 v16, v64, v18
	v_sub_f32_e32 v21, v67, v18
	v_sub_f32_e32 v20, v66, v18
	v_pk_mul_f32 v[20:21], v[18:19], v[20:21] op_sel:[1,0]
	v_pk_mul_f32 v[16:17], v[18:19], v[16:17] op_sel:[1,0]
	v_pk_fma_f32 v[18:19], v[206:207], v[20:21], v[210:211]
	v_pk_fma_f32 v[16:17], v[204:205], v[16:17], v[208:209]
	v_cndmask_b32_e32 v19, v147, v19, vcc
	v_cndmask_b32_e32 v18, v147, v18, vcc
	v_cndmask_b32_e32 v17, v147, v17, vcc
	v_cndmask_b32_e32 v16, v147, v16, vcc
	v_lshl_add_u64 v[20:21], v[128:129], 2, s[4:5]
	global_store_dwordx4 v[20:21], v[16:19], off nt
	s_nop 1
	v_cvt_pk_bf16_f32 v16, v16, v17
	v_cvt_pk_bf16_f32 v17, v18, v19
	v_lshl_add_u64 v[18:19], v[128:129], 1, s[6:7]
	global_store_dwordx2 v[18:19], v[16:17], off
	ds_read_b64 v[24:25], v139 offset:8192
	v_lshl_add_u32 v26, v146, 11, v138
	v_add_u32_e32 v128, 0x90, v26
	s_waitcnt lgkmcnt(0)
	v_sub_f32_e32 v13, v13, v24
	v_sub_f32_e32 v12, v12, v24
	v_sub_f32_e32 v15, v15, v24
	v_sub_f32_e32 v14, v14, v24
	v_pk_mul_f32 v[14:15], v[24:25], v[14:15] op_sel:[1,0]
	v_pk_mul_f32 v[12:13], v[24:25], v[12:13] op_sel:[1,0]
	v_lshl_add_u64 v[24:25], v[128:129], 2, s[4:5]
	v_pk_fma_f32 v[12:13], v[212:213], v[12:13], v[160:161]
	v_pk_fma_f32 v[14:15], v[214:215], v[14:15], v[162:163]
	v_cndmask_b32_e32 v13, v147, v13, vcc
	v_cndmask_b32_e32 v15, v147, v15, vcc
	v_cndmask_b32_e32 v14, v147, v14, vcc
	v_cndmask_b32_e32 v12, v147, v12, vcc
	global_store_dwordx4 v[24:25], v[12:15], off nt
	v_lshl_add_u64 v[24:25], v[128:129], 1, s[6:7]
	v_add_u32_e32 v128, 0x8090, v26
	v_cvt_pk_bf16_f32 v12, v12, v13
	v_cvt_pk_bf16_f32 v13, v14, v15
	ds_read_b64 v[14:15], v139 offset:8320
	global_store_dwordx2 v[24:25], v[12:13], off
	v_lshl_add_u64 v[12:13], v[128:129], 2, s[4:5]
	s_waitcnt lgkmcnt(0)
	v_sub_f32_e32 v9, v9, v14
	v_sub_f32_e32 v8, v8, v14
	v_sub_f32_e32 v11, v11, v14
	v_sub_f32_e32 v10, v10, v14
	v_pk_mul_f32 v[10:11], v[14:15], v[10:11] op_sel:[1,0]
	v_pk_mul_f32 v[8:9], v[14:15], v[8:9] op_sel:[1,0]
	v_pk_fma_f32 v[10:11], v[214:215], v[10:11], v[162:163]
	v_pk_fma_f32 v[8:9], v[212:213], v[8:9], v[160:161]
	v_cndmask_b32_e32 v11, v147, v11, vcc
	v_cndmask_b32_e32 v10, v147, v10, vcc
	v_cndmask_b32_e32 v9, v147, v9, vcc
	v_cndmask_b32_e32 v8, v147, v8, vcc
	global_store_dwordx4 v[12:13], v[8:11], off nt
	v_lshl_add_u64 v[12:13], v[128:129], 1, s[6:7]
	v_add_u32_e32 v128, 0x10090, v26
	v_cvt_pk_bf16_f32 v8, v8, v9
	v_cvt_pk_bf16_f32 v9, v10, v11
	ds_read_b64 v[10:11], v139 offset:8448
	global_store_dwordx2 v[12:13], v[8:9], off
	v_lshl_add_u64 v[8:9], v[128:129], 2, s[4:5]
	s_waitcnt lgkmcnt(0)
	v_sub_f32_e32 v5, v5, v10
	v_sub_f32_e32 v4, v4, v10
	v_sub_f32_e32 v7, v7, v10
	v_sub_f32_e32 v6, v6, v10
	v_pk_mul_f32 v[6:7], v[10:11], v[6:7] op_sel:[1,0]
	v_pk_mul_f32 v[4:5], v[10:11], v[4:5] op_sel:[1,0]
	v_pk_fma_f32 v[6:7], v[214:215], v[6:7], v[162:163]
	v_pk_fma_f32 v[4:5], v[212:213], v[4:5], v[160:161]
	v_cndmask_b32_e32 v7, v147, v7, vcc
	v_cndmask_b32_e32 v6, v147, v6, vcc
	v_cndmask_b32_e32 v5, v147, v5, vcc
	v_cndmask_b32_e32 v4, v147, v4, vcc
	global_store_dwordx4 v[8:9], v[4:7], off nt
	v_lshl_add_u64 v[8:9], v[128:129], 1, s[6:7]
	v_add_u32_e32 v128, 0x18090, v26
	v_cvt_pk_bf16_f32 v4, v4, v5
	v_cvt_pk_bf16_f32 v5, v6, v7
	ds_read_b64 v[6:7], v139 offset:8576
	global_store_dwordx2 v[8:9], v[4:5], off
	v_lshl_add_u64 v[4:5], v[128:129], 2, s[4:5]
	s_waitcnt lgkmcnt(0)
	v_sub_f32_e32 v1, v1, v6
	v_sub_f32_e32 v0, v0, v6
	v_sub_f32_e32 v3, v3, v6
	v_sub_f32_e32 v2, v2, v6
	v_pk_mul_f32 v[2:3], v[6:7], v[2:3] op_sel:[1,0]
	v_pk_mul_f32 v[0:1], v[6:7], v[0:1] op_sel:[1,0]
	v_pk_fma_f32 v[2:3], v[214:215], v[2:3], v[162:163]
	v_pk_fma_f32 v[0:1], v[212:213], v[0:1], v[160:161]
	v_cndmask_b32_e32 v3, v147, v3, vcc
	v_cndmask_b32_e32 v2, v147, v2, vcc
	v_cndmask_b32_e32 v1, v147, v1, vcc
	v_cndmask_b32_e32 v0, v147, v0, vcc
	global_store_dwordx4 v[4:5], v[0:3], off nt
	v_lshl_add_u64 v[4:5], v[128:129], 1, s[6:7]
	v_add_u32_e32 v128, 0x40090, v26
	v_cvt_pk_bf16_f32 v0, v0, v1
	v_cvt_pk_bf16_f32 v1, v2, v3
	ds_read_b64 v[2:3], v139 offset:9216
	global_store_dwordx2 v[4:5], v[0:1], off
	s_waitcnt lgkmcnt(0)
	v_sub_f32_e32 v1, v45, v2
	v_sub_f32_e32 v0, v44, v2
	v_sub_f32_e32 v5, v47, v2
	v_sub_f32_e32 v4, v46, v2
	v_pk_mul_f32 v[4:5], v[2:3], v[4:5] op_sel:[1,0]
	v_pk_mul_f32 v[0:1], v[2:3], v[0:1] op_sel:[1,0]
	v_pk_fma_f32 v[2:3], v[214:215], v[4:5], v[162:163]
	v_pk_fma_f32 v[0:1], v[212:213], v[0:1], v[160:161]
	v_cndmask_b32_e32 v3, v147, v3, vcc
	v_cndmask_b32_e32 v2, v147, v2, vcc
	v_cndmask_b32_e32 v1, v147, v1, vcc
	v_cndmask_b32_e32 v0, v147, v0, vcc
	v_lshl_add_u64 v[4:5], v[128:129], 2, s[4:5]
	global_store_dwordx4 v[4:5], v[0:3], off nt
	v_lshl_add_u64 v[4:5], v[128:129], 1, s[6:7]
	v_add_u32_e32 v128, 0x48090, v26
	v_cvt_pk_bf16_f32 v0, v0, v1
	v_cvt_pk_bf16_f32 v1, v2, v3
	ds_read_b64 v[2:3], v139 offset:9344
	global_store_dwordx2 v[4:5], v[0:1], off
	s_waitcnt lgkmcnt(0)
	v_sub_f32_e32 v1, v41, v2
	v_sub_f32_e32 v0, v40, v2
	v_sub_f32_e32 v5, v43, v2
	v_sub_f32_e32 v4, v42, v2
	v_pk_mul_f32 v[4:5], v[2:3], v[4:5] op_sel:[1,0]
	v_pk_mul_f32 v[0:1], v[2:3], v[0:1] op_sel:[1,0]
	v_pk_fma_f32 v[2:3], v[214:215], v[4:5], v[162:163]
	v_pk_fma_f32 v[0:1], v[212:213], v[0:1], v[160:161]
	v_cndmask_b32_e32 v3, v147, v3, vcc
	v_cndmask_b32_e32 v2, v147, v2, vcc
	v_cndmask_b32_e32 v1, v147, v1, vcc
	v_cndmask_b32_e32 v0, v147, v0, vcc
	v_lshl_add_u64 v[4:5], v[128:129], 2, s[4:5]
	global_store_dwordx4 v[4:5], v[0:3], off nt
	v_lshl_add_u64 v[4:5], v[128:129], 1, s[6:7]
	v_add_u32_e32 v128, 0x50090, v26
	v_cvt_pk_bf16_f32 v0, v0, v1
	v_cvt_pk_bf16_f32 v1, v2, v3
	ds_read_b64 v[2:3], v139 offset:9472
	global_store_dwordx2 v[4:5], v[0:1], off
	s_waitcnt lgkmcnt(0)
	v_sub_f32_e32 v1, v37, v2
	v_sub_f32_e32 v0, v36, v2
	v_sub_f32_e32 v5, v39, v2
	v_sub_f32_e32 v4, v38, v2
	v_pk_mul_f32 v[4:5], v[2:3], v[4:5] op_sel:[1,0]
	v_pk_mul_f32 v[0:1], v[2:3], v[0:1] op_sel:[1,0]
	v_pk_fma_f32 v[2:3], v[214:215], v[4:5], v[162:163]
	v_pk_fma_f32 v[0:1], v[212:213], v[0:1], v[160:161]
	v_cndmask_b32_e32 v3, v147, v3, vcc
	v_cndmask_b32_e32 v2, v147, v2, vcc
	v_cndmask_b32_e32 v1, v147, v1, vcc
	v_cndmask_b32_e32 v0, v147, v0, vcc
	v_lshl_add_u64 v[4:5], v[128:129], 2, s[4:5]
	global_store_dwordx4 v[4:5], v[0:3], off nt
	v_lshl_add_u64 v[4:5], v[128:129], 1, s[6:7]
	v_add_u32_e32 v128, 0x58090, v26
	v_cvt_pk_bf16_f32 v0, v0, v1
	v_cvt_pk_bf16_f32 v1, v2, v3
	ds_read_b64 v[2:3], v139 offset:9600
	global_store_dwordx2 v[4:5], v[0:1], off
	s_waitcnt lgkmcnt(0)
	v_sub_f32_e32 v1, v33, v2
	v_sub_f32_e32 v0, v32, v2
	v_sub_f32_e32 v5, v35, v2
	v_sub_f32_e32 v4, v34, v2
	v_pk_mul_f32 v[4:5], v[2:3], v[4:5] op_sel:[1,0]
	v_pk_mul_f32 v[0:1], v[2:3], v[0:1] op_sel:[1,0]
	v_pk_fma_f32 v[2:3], v[214:215], v[4:5], v[162:163]
	v_pk_fma_f32 v[0:1], v[212:213], v[0:1], v[160:161]
	v_cndmask_b32_e32 v3, v147, v3, vcc
	v_cndmask_b32_e32 v2, v147, v2, vcc
	v_cndmask_b32_e32 v1, v147, v1, vcc
	v_cndmask_b32_e32 v0, v147, v0, vcc
	v_lshl_add_u64 v[4:5], v[128:129], 2, s[4:5]
	global_store_dwordx4 v[4:5], v[0:3], off nt
	s_nop 1
	v_cvt_pk_bf16_f32 v0, v0, v1
	v_cvt_pk_bf16_f32 v1, v2, v3
	v_lshl_add_u64 v[2:3], v[128:129], 1, s[6:7]
	global_store_dwordx2 v[2:3], v[0:1], off

.LBB0_166:
	s_or_b64 exec, exec, s[6:7]
	v_readlane_b32 s4, v255, 7
	v_readlane_b32 s5, v255, 8
	s_lshl_b32 s4, s4, 11
	s_ashr_i32 s5, s4, 31
	v_readlane_b32 s36, v254, 35
	s_lshl_b64 s[4:5], s[4:5], 2
	v_readlane_b32 s38, v254, 37
	v_readlane_b32 s39, v254, 38
	s_add_u32 s6, s38, s4
	v_readlane_b32 s40, v254, 39
	s_addc_u32 s7, s39, s5
	v_readlane_b32 s41, v254, 40
	s_add_u32 s4, s40, s4
	v_mov_b32_e32 v139, v129
	s_addc_u32 s5, s41, s5
	v_lshlrev_b64 v[134:135], 2, v[138:139]
	v_lshl_add_u64 v[140:141], s[6:7], 0, v[134:135]
	v_lshl_add_u64 v[142:143], s[4:5], 0, v[134:135]
	s_waitcnt lgkmcnt(0)
	s_barrier
	global_load_dwordx4 v[130:133], v[140:141], off
	global_load_dwordx4 v[134:137], v[142:143], off
	global_load_dwordx4 v[196:199], v[140:141], off offset:64
	global_load_dwordx4 v[200:203], v[142:143], off offset:64
	global_load_dwordx4 v[204:207], v[140:141], off offset:512
	global_load_dwordx4 v[208:211], v[142:143], off offset:512
	global_load_dwordx4 v[212:215], v[140:141], off offset:576
	global_load_dwordx4 v[160:163], v[142:143], off offset:576
	s_lshl_b32 s4, s24, 3
	s_add_i32 s4, s4, 0
	v_lshl_add_u32 v139, v144, 3, s4
	ds_read_b64 v[152:153], v139 offset:8192
	s_waitcnt lgkmcnt(0)
	v_cmp_eq_u32_e32 vcc, 0, v128
	v_lshl_add_u32 v128, v146, 11, v138
	v_mov_b32_e32 v147, 0x7fc00000
	v_lshl_add_u64 v[156:157], v[128:129], 2, s[0:1]
	v_sub_f32_e32 v93, v93, v152
	v_sub_f32_e32 v92, v92, v152
	v_sub_f32_e32 v95, v95, v152
	v_sub_f32_e32 v94, v94, v152
	v_pk_mul_f32 v[94:95], v[152:153], v[94:95] op_sel:[1,0]
	v_pk_mul_f32 v[92:93], v[152:153], v[92:93] op_sel:[1,0]
	v_readlane_b32 s4, v255, 9
	v_mov_b32_e32 v145, v129
	v_readlane_b32 s5, v255, 10
	v_add_u32_e32 v144, 0x8000, v128
	v_mov_b32_e32 v149, v129
	v_lshl_add_u64 v[152:153], v[128:129], 1, s[4:5]
	v_add_u32_e32 v148, 0x10000, v128
	v_mov_b32_e32 v151, v129
	v_add_u32_e32 v150, 0x18000, v128
	v_mov_b32_e32 v155, v129
	v_add_u32_e32 v154, 0x40000, v128
	v_readlane_b32 s37, v254, 36
	v_readlane_b32 s42, v254, 41
	v_readlane_b32 s43, v254, 42
	v_readlane_b32 s44, v254, 43
	v_readlane_b32 s45, v254, 44
	v_readlane_b32 s46, v254, 45
	v_readlane_b32 s47, v254, 46
	v_readlane_b32 s48, v254, 47
	v_readlane_b32 s49, v254, 48
	v_readlane_b32 s50, v254, 49
	v_readlane_b32 s51, v254, 50
	s_waitcnt vmcnt(0)
	v_pk_fma_f32 v[92:93], v[130:131], v[92:93], v[134:135]
	v_pk_fma_f32 v[94:95], v[132:133], v[94:95], v[136:137]
	v_cndmask_b32_e32 v93, v147, v93, vcc
	v_cndmask_b32_e32 v95, v147, v95, vcc
	v_cndmask_b32_e32 v94, v147, v94, vcc
	v_cndmask_b32_e32 v92, v147, v92, vcc
	global_store_dwordx4 v[156:157], v[92:95], off nt
	v_lshl_add_u64 v[156:157], v[144:145], 2, s[0:1]
	s_nop 0
	v_cvt_pk_bf16_f32 v92, v92, v93
	v_cvt_pk_bf16_f32 v93, v94, v95
	ds_read_b64 v[94:95], v139 offset:8320
	global_store_dwordx2 v[152:153], v[92:93], off
	v_lshl_add_u64 v[92:93], v[144:145], 1, s[4:5]
	s_waitcnt lgkmcnt(0)
	v_sub_f32_e32 v89, v89, v94
	v_sub_f32_e32 v88, v88, v94
	v_sub_f32_e32 v91, v91, v94
	v_sub_f32_e32 v90, v90, v94
	v_pk_mul_f32 v[90:91], v[94:95], v[90:91] op_sel:[1,0]
	v_pk_mul_f32 v[88:89], v[94:95], v[88:89] op_sel:[1,0]
	v_pk_fma_f32 v[90:91], v[132:133], v[90:91], v[136:137]
	v_pk_fma_f32 v[88:89], v[130:131], v[88:89], v[134:135]
	v_cndmask_b32_e32 v91, v147, v91, vcc
	v_cndmask_b32_e32 v90, v147, v90, vcc
	v_cndmask_b32_e32 v89, v147, v89, vcc
	v_cndmask_b32_e32 v88, v147, v88, vcc
	global_store_dwordx4 v[156:157], v[88:91], off nt
	v_lshl_add_u64 v[94:95], v[148:149], 2, s[0:1]
	s_nop 0
	v_cvt_pk_bf16_f32 v88, v88, v89
	v_cvt_pk_bf16_f32 v89, v90, v91
	ds_read_b64 v[90:91], v139 offset:8448
	global_store_dwordx2 v[92:93], v[88:89], off
	v_lshl_add_u64 v[88:89], v[148:149], 1, s[4:5]
	s_waitcnt lgkmcnt(0)
	v_sub_f32_e32 v85, v85, v90
	v_sub_f32_e32 v84, v84, v90
	v_sub_f32_e32 v87, v87, v90
	v_sub_f32_e32 v86, v86, v90
	v_pk_mul_f32 v[86:87], v[90:91], v[86:87] op_sel:[1,0]
	v_pk_mul_f32 v[84:85], v[90:91], v[84:85] op_sel:[1,0]
	v_pk_fma_f32 v[86:87], v[132:133], v[86:87], v[136:137]
	v_pk_fma_f32 v[84:85], v[130:131], v[84:85], v[134:135]
	v_cndmask_b32_e32 v87, v147, v87, vcc
	v_cndmask_b32_e32 v86, v147, v86, vcc
	v_cndmask_b32_e32 v85, v147, v85, vcc
	v_cndmask_b32_e32 v84, v147, v84, vcc
	global_store_dwordx4 v[94:95], v[84:87], off nt
	v_lshl_add_u64 v[90:91], v[150:151], 2, s[0:1]
	s_nop 0
	v_cvt_pk_bf16_f32 v84, v84, v85
	v_cvt_pk_bf16_f32 v85, v86, v87
	ds_read_b64 v[86:87], v139 offset:8576
	global_store_dwordx2 v[88:89], v[84:85], off
	v_lshl_add_u64 v[84:85], v[150:151], 1, s[4:5]
	s_waitcnt lgkmcnt(0)
	v_sub_f32_e32 v81, v81, v86
	v_sub_f32_e32 v80, v80, v86
	v_sub_f32_e32 v83, v83, v86
	v_sub_f32_e32 v82, v82, v86
	v_pk_mul_f32 v[82:83], v[86:87], v[82:83] op_sel:[1,0]
	v_pk_mul_f32 v[80:81], v[86:87], v[80:81] op_sel:[1,0]
	v_pk_fma_f32 v[82:83], v[132:133], v[82:83], v[136:137]
	v_pk_fma_f32 v[80:81], v[130:131], v[80:81], v[134:135]
	v_cndmask_b32_e32 v83, v147, v83, vcc
	v_cndmask_b32_e32 v82, v147, v82, vcc
	v_cndmask_b32_e32 v81, v147, v81, vcc
	v_cndmask_b32_e32 v80, v147, v80, vcc
	global_store_dwordx4 v[90:91], v[80:83], off nt
	v_lshl_add_u64 v[86:87], v[154:155], 2, s[0:1]
	s_nop 0
	v_cvt_pk_bf16_f32 v80, v80, v81
	v_cvt_pk_bf16_f32 v81, v82, v83
	ds_read_b64 v[82:83], v139 offset:9216
	global_store_dwordx2 v[84:85], v[80:81], off
	s_waitcnt lgkmcnt(0)
	v_sub_f32_e32 v81, v125, v82
	v_sub_f32_e32 v80, v124, v82
	v_sub_f32_e32 v85, v127, v82
	v_sub_f32_e32 v84, v126, v82
	v_pk_mul_f32 v[84:85], v[82:83], v[84:85] op_sel:[1,0]
	v_pk_mul_f32 v[80:81], v[82:83], v[80:81] op_sel:[1,0]
	v_pk_fma_f32 v[82:83], v[132:133], v[84:85], v[136:137]
	v_pk_fma_f32 v[80:81], v[130:131], v[80:81], v[134:135]
	v_cndmask_b32_e32 v83, v147, v83, vcc
	v_cndmask_b32_e32 v82, v147, v82, vcc
	v_cndmask_b32_e32 v81, v147, v81, vcc
	v_cndmask_b32_e32 v80, v147, v80, vcc
	global_store_dwordx4 v[86:87], v[80:83], off nt
	v_lshl_add_u64 v[86:87], v[154:155], 1, s[4:5]
	v_add_u32_e32 v84, 0x48000, v128
	v_cvt_pk_bf16_f32 v80, v80, v81
	v_cvt_pk_bf16_f32 v81, v82, v83
	ds_read_b64 v[82:83], v139 offset:9344
	global_store_dwordx2 v[86:87], v[80:81], off
	v_mov_b32_e32 v85, v129
	s_waitcnt lgkmcnt(0)
	v_sub_f32_e32 v81, v121, v82
	v_sub_f32_e32 v80, v120, v82
	v_sub_f32_e32 v87, v123, v82
	v_sub_f32_e32 v86, v122, v82
	v_pk_mul_f32 v[86:87], v[82:83], v[86:87] op_sel:[1,0]
	v_pk_mul_f32 v[80:81], v[82:83], v[80:81] op_sel:[1,0]
	v_pk_fma_f32 v[82:83], v[132:133], v[86:87], v[136:137]
	v_pk_fma_f32 v[80:81], v[130:131], v[80:81], v[134:135]
	v_cndmask_b32_e32 v83, v147, v83, vcc
	v_cndmask_b32_e32 v82, v147, v82, vcc
	v_cndmask_b32_e32 v81, v147, v81, vcc
	v_cndmask_b32_e32 v80, v147, v80, vcc
	v_lshl_add_u64 v[86:87], v[84:85], 2, s[0:1]
	global_store_dwordx4 v[86:87], v[80:83], off nt
	v_lshl_add_u64 v[84:85], v[84:85], 1, s[4:5]
	s_nop 0
	v_cvt_pk_bf16_f32 v80, v80, v81
	v_cvt_pk_bf16_f32 v81, v82, v83
	ds_read_b64 v[82:83], v139 offset:9472
	global_store_dwordx2 v[84:85], v[80:81], off
	v_add_u32_e32 v84, 0x50000, v128
	v_mov_b32_e32 v85, v129
	v_add_u32_e32 v128, 0x58000, v128
	s_waitcnt lgkmcnt(0)
	v_sub_f32_e32 v81, v117, v82
	v_sub_f32_e32 v80, v116, v82
	v_sub_f32_e32 v87, v119, v82
	v_sub_f32_e32 v86, v118, v82
	v_pk_mul_f32 v[86:87], v[82:83], v[86:87] op_sel:[1,0]
	v_pk_mul_f32 v[80:81], v[82:83], v[80:81] op_sel:[1,0]
	v_pk_fma_f32 v[82:83], v[132:133], v[86:87], v[136:137]
	v_pk_fma_f32 v[80:81], v[130:131], v[80:81], v[134:135]
	v_cndmask_b32_e32 v83, v147, v83, vcc
	v_cndmask_b32_e32 v82, v147, v82, vcc
	v_cndmask_b32_e32 v81, v147, v81, vcc
	v_cndmask_b32_e32 v80, v147, v80, vcc
	v_lshl_add_u64 v[86:87], v[84:85], 2, s[0:1]
	global_store_dwordx4 v[86:87], v[80:83], off nt
	v_lshl_add_u64 v[84:85], v[84:85], 1, s[4:5]
	s_nop 0
	v_cvt_pk_bf16_f32 v80, v80, v81
	v_cvt_pk_bf16_f32 v81, v82, v83
	ds_read_b64 v[82:83], v139 offset:9600
	global_store_dwordx2 v[84:85], v[80:81], off
	s_waitcnt lgkmcnt(0)
	v_sub_f32_e32 v81, v113, v82
	v_sub_f32_e32 v80, v112, v82
	v_sub_f32_e32 v85, v115, v82
	v_sub_f32_e32 v84, v114, v82
	v_pk_mul_f32 v[84:85], v[82:83], v[84:85] op_sel:[1,0]
	v_pk_mul_f32 v[80:81], v[82:83], v[80:81] op_sel:[1,0]
	v_pk_fma_f32 v[82:83], v[132:133], v[84:85], v[136:137]
	v_pk_fma_f32 v[80:81], v[130:131], v[80:81], v[134:135]
	v_cndmask_b32_e32 v83, v147, v83, vcc
	v_cndmask_b32_e32 v82, v147, v82, vcc
	v_cndmask_b32_e32 v81, v147, v81, vcc
	v_cndmask_b32_e32 v80, v147, v80, vcc
	v_lshl_add_u64 v[84:85], v[128:129], 2, s[0:1]
	global_store_dwordx4 v[84:85], v[80:83], off nt
	s_nop 1
	v_cvt_pk_bf16_f32 v80, v80, v81
	v_cvt_pk_bf16_f32 v81, v82, v83
	v_lshl_add_u64 v[82:83], v[128:129], 1, s[4:5]
	global_store_dwordx2 v[82:83], v[80:81], off
	ds_read_b64 v[88:89], v139 offset:8192
	v_lshl_add_u32 v92, v146, 11, v138
	v_add_u32_e32 v128, 16, v92
	v_lshl_add_u64 v[90:91], v[128:129], 2, s[0:1]
	s_waitcnt lgkmcnt(0)
	v_sub_f32_e32 v61, v61, v88
	v_sub_f32_e32 v60, v60, v88
	v_sub_f32_e32 v63, v63, v88
	v_sub_f32_e32 v62, v62, v88
	v_pk_mul_f32 v[62:63], v[88:89], v[62:63] op_sel:[1,0]
	v_pk_mul_f32 v[60:61], v[88:89], v[60:61] op_sel:[1,0]
	v_lshl_add_u64 v[88:89], v[128:129], 1, s[4:5]
	v_add_u32_e32 v128, 0x8010, v92
	v_pk_fma_f32 v[60:61], v[196:197], v[60:61], v[200:201]
	v_pk_fma_f32 v[62:63], v[198:199], v[62:63], v[202:203]
	v_cndmask_b32_e32 v61, v147, v61, vcc
	v_cndmask_b32_e32 v63, v147, v63, vcc
	v_cndmask_b32_e32 v62, v147, v62, vcc
	v_cndmask_b32_e32 v60, v147, v60, vcc
	global_store_dwordx4 v[90:91], v[60:63], off nt
	v_lshl_add_u64 v[90:91], v[128:129], 2, s[0:1]
	s_nop 0
	v_cvt_pk_bf16_f32 v60, v60, v61
	v_cvt_pk_bf16_f32 v61, v62, v63
	ds_read_b64 v[62:63], v139 offset:8320
	global_store_dwordx2 v[88:89], v[60:61], off
	v_lshl_add_u64 v[60:61], v[128:129], 1, s[4:5]
	v_add_u32_e32 v128, 0x10010, v92
	s_waitcnt lgkmcnt(0)
	v_sub_f32_e32 v57, v57, v62
	v_sub_f32_e32 v56, v56, v62
	v_sub_f32_e32 v59, v59, v62
	v_sub_f32_e32 v58, v58, v62
	v_pk_mul_f32 v[58:59], v[62:63], v[58:59] op_sel:[1,0]
	v_pk_mul_f32 v[56:57], v[62:63], v[56:57] op_sel:[1,0]
	v_pk_fma_f32 v[58:59], v[198:199], v[58:59], v[202:203]
	v_pk_fma_f32 v[56:57], v[196:197], v[56:57], v[200:201]
	v_cndmask_b32_e32 v59, v147, v59, vcc
	v_cndmask_b32_e32 v58, v147, v58, vcc
	v_cndmask_b32_e32 v57, v147, v57, vcc
	v_cndmask_b32_e32 v56, v147, v56, vcc
	global_store_dwordx4 v[90:91], v[56:59], off nt
	v_lshl_add_u64 v[62:63], v[128:129], 2, s[0:1]
	s_nop 0
	v_cvt_pk_bf16_f32 v56, v56, v57
	v_cvt_pk_bf16_f32 v57, v58, v59
	ds_read_b64 v[58:59], v139 offset:8448
	global_store_dwordx2 v[60:61], v[56:57], off
	v_lshl_add_u64 v[56:57], v[128:129], 1, s[4:5]
	v_add_u32_e32 v128, 0x18010, v92
	s_waitcnt lgkmcnt(0)
	v_sub_f32_e32 v53, v53, v58
	v_sub_f32_e32 v52, v52, v58
	v_sub_f32_e32 v55, v55, v58
	v_sub_f32_e32 v54, v54, v58
	v_pk_mul_f32 v[54:55], v[58:59], v[54:55] op_sel:[1,0]
	v_pk_mul_f32 v[52:53], v[58:59], v[52:53] op_sel:[1,0]
	v_pk_fma_f32 v[54:55], v[198:199], v[54:55], v[202:203]
	v_pk_fma_f32 v[52:53], v[196:197], v[52:53], v[200:201]
	v_cndmask_b32_e32 v55, v147, v55, vcc
	v_cndmask_b32_e32 v54, v147, v54, vcc
	v_cndmask_b32_e32 v53, v147, v53, vcc
	v_cndmask_b32_e32 v52, v147, v52, vcc
	global_store_dwordx4 v[62:63], v[52:55], off nt
	s_nop 1
	v_cvt_pk_bf16_f32 v52, v52, v53
	v_cvt_pk_bf16_f32 v53, v54, v55
	ds_read_b64 v[54:55], v139 offset:8576
	global_store_dwordx2 v[56:57], v[52:53], off
	v_lshl_add_u64 v[52:53], v[128:129], 2, s[0:1]
	s_waitcnt lgkmcnt(0)
	v_sub_f32_e32 v49, v49, v54
	v_sub_f32_e32 v48, v48, v54
	v_sub_f32_e32 v51, v51, v54
	v_sub_f32_e32 v50, v50, v54
	v_pk_mul_f32 v[50:51], v[54:55], v[50:51] op_sel:[1,0]
	v_pk_mul_f32 v[48:49], v[54:55], v[48:49] op_sel:[1,0]
	v_pk_fma_f32 v[50:51], v[198:199], v[50:51], v[202:203]
	v_pk_fma_f32 v[48:49], v[196:197], v[48:49], v[200:201]
	v_cndmask_b32_e32 v51, v147, v51, vcc
	v_cndmask_b32_e32 v50, v147, v50, vcc
	v_cndmask_b32_e32 v49, v147, v49, vcc
	v_cndmask_b32_e32 v48, v147, v48, vcc
	global_store_dwordx4 v[52:53], v[48:51], off nt
	v_lshl_add_u64 v[52:53], v[128:129], 1, s[4:5]
	v_add_u32_e32 v128, 0x40010, v92
	v_cvt_pk_bf16_f32 v48, v48, v49
	v_cvt_pk_bf16_f32 v49, v50, v51
	ds_read_b64 v[50:51], v139 offset:9216
	global_store_dwordx2 v[52:53], v[48:49], off
	s_waitcnt lgkmcnt(0)
	v_sub_f32_e32 v49, v109, v50
	v_sub_f32_e32 v48, v108, v50
	v_sub_f32_e32 v53, v111, v50
	v_sub_f32_e32 v52, v110, v50
	v_pk_mul_f32 v[52:53], v[50:51], v[52:53] op_sel:[1,0]
	v_pk_mul_f32 v[48:49], v[50:51], v[48:49] op_sel:[1,0]
	v_pk_fma_f32 v[50:51], v[198:199], v[52:53], v[202:203]
	v_pk_fma_f32 v[48:49], v[196:197], v[48:49], v[200:201]
	v_cndmask_b32_e32 v51, v147, v51, vcc
	v_cndmask_b32_e32 v50, v147, v50, vcc
	v_cndmask_b32_e32 v49, v147, v49, vcc
	v_cndmask_b32_e32 v48, v147, v48, vcc
	v_lshl_add_u64 v[52:53], v[128:129], 2, s[0:1]
	global_store_dwordx4 v[52:53], v[48:51], off nt
	v_lshl_add_u64 v[52:53], v[128:129], 1, s[4:5]
	v_add_u32_e32 v128, 0x48010, v92
	v_cvt_pk_bf16_f32 v48, v48, v49
	v_cvt_pk_bf16_f32 v49, v50, v51
	ds_read_b64 v[50:51], v139 offset:9344
	global_store_dwordx2 v[52:53], v[48:49], off
	s_waitcnt lgkmcnt(0)
	v_sub_f32_e32 v49, v105, v50
	v_sub_f32_e32 v48, v104, v50
	v_sub_f32_e32 v53, v107, v50
	v_sub_f32_e32 v52, v106, v50
	v_pk_mul_f32 v[52:53], v[50:51], v[52:53] op_sel:[1,0]
	v_pk_mul_f32 v[48:49], v[50:51], v[48:49] op_sel:[1,0]
	v_pk_fma_f32 v[50:51], v[198:199], v[52:53], v[202:203]
	v_pk_fma_f32 v[48:49], v[196:197], v[48:49], v[200:201]
	v_cndmask_b32_e32 v51, v147, v51, vcc
	v_cndmask_b32_e32 v50, v147, v50, vcc
	v_cndmask_b32_e32 v49, v147, v49, vcc
	v_cndmask_b32_e32 v48, v147, v48, vcc
	v_lshl_add_u64 v[52:53], v[128:129], 2, s[0:1]
	global_store_dwordx4 v[52:53], v[48:51], off nt
	v_lshl_add_u64 v[52:53], v[128:129], 1, s[4:5]
	v_add_u32_e32 v128, 0x50010, v92
	v_cvt_pk_bf16_f32 v48, v48, v49
	v_cvt_pk_bf16_f32 v49, v50, v51
	ds_read_b64 v[50:51], v139 offset:9472
	global_store_dwordx2 v[52:53], v[48:49], off
	s_waitcnt lgkmcnt(0)
	v_sub_f32_e32 v49, v101, v50
	v_sub_f32_e32 v48, v100, v50
	v_sub_f32_e32 v53, v103, v50
	v_sub_f32_e32 v52, v102, v50
	v_pk_mul_f32 v[52:53], v[50:51], v[52:53] op_sel:[1,0]
	v_pk_mul_f32 v[48:49], v[50:51], v[48:49] op_sel:[1,0]
	v_pk_fma_f32 v[50:51], v[198:199], v[52:53], v[202:203]
	v_pk_fma_f32 v[48:49], v[196:197], v[48:49], v[200:201]
	v_cndmask_b32_e32 v51, v147, v51, vcc
	v_cndmask_b32_e32 v50, v147, v50, vcc
	v_cndmask_b32_e32 v49, v147, v49, vcc
	v_cndmask_b32_e32 v48, v147, v48, vcc
	v_lshl_add_u64 v[52:53], v[128:129], 2, s[0:1]
	global_store_dwordx4 v[52:53], v[48:51], off nt
	v_lshl_add_u64 v[52:53], v[128:129], 1, s[4:5]
	v_add_u32_e32 v128, 0x58010, v92
	v_cvt_pk_bf16_f32 v48, v48, v49
	v_cvt_pk_bf16_f32 v49, v50, v51
	ds_read_b64 v[50:51], v139 offset:9600
	global_store_dwordx2 v[52:53], v[48:49], off
	s_waitcnt lgkmcnt(0)
	v_sub_f32_e32 v49, v97, v50
	v_sub_f32_e32 v48, v96, v50
	v_sub_f32_e32 v53, v99, v50
	v_sub_f32_e32 v52, v98, v50
	v_pk_mul_f32 v[52:53], v[50:51], v[52:53] op_sel:[1,0]
	v_pk_mul_f32 v[48:49], v[50:51], v[48:49] op_sel:[1,0]
	v_pk_fma_f32 v[50:51], v[198:199], v[52:53], v[202:203]
	v_pk_fma_f32 v[48:49], v[196:197], v[48:49], v[200:201]
	v_cndmask_b32_e32 v51, v147, v51, vcc
	v_cndmask_b32_e32 v50, v147, v50, vcc
	v_cndmask_b32_e32 v49, v147, v49, vcc
	v_cndmask_b32_e32 v48, v147, v48, vcc
	v_lshl_add_u64 v[52:53], v[128:129], 2, s[0:1]
	global_store_dwordx4 v[52:53], v[48:51], off nt
	s_nop 1
	v_cvt_pk_bf16_f32 v48, v48, v49
	v_cvt_pk_bf16_f32 v49, v50, v51
	v_lshl_add_u64 v[50:51], v[128:129], 1, s[4:5]
	global_store_dwordx2 v[50:51], v[48:49], off
	ds_read_b64 v[56:57], v139 offset:8192
	v_lshl_add_u32 v60, v146, 11, v138
	v_add_u32_e32 v128, 0x80, v60
	v_lshl_add_u64 v[58:59], v[128:129], 2, s[0:1]
	s_waitcnt lgkmcnt(0)
	v_sub_f32_e32 v29, v29, v56
	v_sub_f32_e32 v28, v28, v56
	v_sub_f32_e32 v31, v31, v56
	v_sub_f32_e32 v30, v30, v56
	v_pk_mul_f32 v[30:31], v[56:57], v[30:31] op_sel:[1,0]
	v_pk_mul_f32 v[28:29], v[56:57], v[28:29] op_sel:[1,0]
	v_lshl_add_u64 v[56:57], v[128:129], 1, s[4:5]
	v_add_u32_e32 v128, 0x8080, v60
	v_pk_fma_f32 v[28:29], v[204:205], v[28:29], v[208:209]
	v_pk_fma_f32 v[30:31], v[206:207], v[30:31], v[210:211]
	v_cndmask_b32_e32 v29, v147, v29, vcc
	v_cndmask_b32_e32 v31, v147, v31, vcc
	v_cndmask_b32_e32 v30, v147, v30, vcc
	v_cndmask_b32_e32 v28, v147, v28, vcc
	global_store_dwordx4 v[58:59], v[28:31], off nt
	v_lshl_add_u64 v[58:59], v[128:129], 2, s[0:1]
	s_nop 0
	v_cvt_pk_bf16_f32 v28, v28, v29
	v_cvt_pk_bf16_f32 v29, v30, v31
	ds_read_b64 v[30:31], v139 offset:8320
	global_store_dwordx2 v[56:57], v[28:29], off
	v_lshl_add_u64 v[28:29], v[128:129], 1, s[4:5]
	v_add_u32_e32 v128, 0x10080, v60
	s_waitcnt lgkmcnt(0)
	v_sub_f32_e32 v25, v25, v30
	v_sub_f32_e32 v24, v24, v30
	v_sub_f32_e32 v27, v27, v30
	v_sub_f32_e32 v26, v26, v30
	v_pk_mul_f32 v[26:27], v[30:31], v[26:27] op_sel:[1,0]
	v_pk_mul_f32 v[24:25], v[30:31], v[24:25] op_sel:[1,0]
	v_pk_fma_f32 v[26:27], v[206:207], v[26:27], v[210:211]
	v_pk_fma_f32 v[24:25], v[204:205], v[24:25], v[208:209]
	v_cndmask_b32_e32 v27, v147, v27, vcc
	v_cndmask_b32_e32 v26, v147, v26, vcc
	v_cndmask_b32_e32 v25, v147, v25, vcc
	v_cndmask_b32_e32 v24, v147, v24, vcc
	global_store_dwordx4 v[58:59], v[24:27], off nt
	s_nop 1
	v_cvt_pk_bf16_f32 v24, v24, v25
	v_cvt_pk_bf16_f32 v25, v26, v27
	ds_read_b64 v[26:27], v139 offset:8448
	global_store_dwordx2 v[28:29], v[24:25], off
	v_lshl_add_u64 v[24:25], v[128:129], 2, s[0:1]
	s_waitcnt lgkmcnt(0)
	v_sub_f32_e32 v21, v21, v26
	v_sub_f32_e32 v20, v20, v26
	v_sub_f32_e32 v23, v23, v26
	v_sub_f32_e32 v22, v22, v26
	v_pk_mul_f32 v[22:23], v[26:27], v[22:23] op_sel:[1,0]
	v_pk_mul_f32 v[20:21], v[26:27], v[20:21] op_sel:[1,0]
	v_pk_fma_f32 v[22:23], v[206:207], v[22:23], v[210:211]
	v_pk_fma_f32 v[20:21], v[204:205], v[20:21], v[208:209]
	v_cndmask_b32_e32 v23, v147, v23, vcc
	v_cndmask_b32_e32 v22, v147, v22, vcc
	v_cndmask_b32_e32 v21, v147, v21, vcc
	v_cndmask_b32_e32 v20, v147, v20, vcc
	global_store_dwordx4 v[24:25], v[20:23], off nt
	v_lshl_add_u64 v[24:25], v[128:129], 1, s[4:5]
	v_add_u32_e32 v128, 0x18080, v60
	v_cvt_pk_bf16_f32 v20, v20, v21
	v_cvt_pk_bf16_f32 v21, v22, v23
	ds_read_b64 v[22:23], v139 offset:8576
	global_store_dwordx2 v[24:25], v[20:21], off
	v_lshl_add_u64 v[20:21], v[128:129], 2, s[0:1]
	s_waitcnt lgkmcnt(0)
	v_sub_f32_e32 v17, v17, v22
	v_sub_f32_e32 v16, v16, v22
	v_sub_f32_e32 v19, v19, v22
	v_sub_f32_e32 v18, v18, v22
	v_pk_mul_f32 v[18:19], v[22:23], v[18:19] op_sel:[1,0]
	v_pk_mul_f32 v[16:17], v[22:23], v[16:17] op_sel:[1,0]
	v_pk_fma_f32 v[18:19], v[206:207], v[18:19], v[210:211]
	v_pk_fma_f32 v[16:17], v[204:205], v[16:17], v[208:209]
	v_cndmask_b32_e32 v19, v147, v19, vcc
	v_cndmask_b32_e32 v18, v147, v18, vcc
	v_cndmask_b32_e32 v17, v147, v17, vcc
	v_cndmask_b32_e32 v16, v147, v16, vcc
	global_store_dwordx4 v[20:21], v[16:19], off nt
	v_lshl_add_u64 v[20:21], v[128:129], 1, s[4:5]
	v_add_u32_e32 v128, 0x40080, v60
	v_cvt_pk_bf16_f32 v16, v16, v17
	v_cvt_pk_bf16_f32 v17, v18, v19
	ds_read_b64 v[18:19], v139 offset:9216
	global_store_dwordx2 v[20:21], v[16:17], off
	s_waitcnt lgkmcnt(0)
	v_sub_f32_e32 v17, v77, v18
	v_sub_f32_e32 v16, v76, v18
	v_sub_f32_e32 v21, v79, v18
	v_sub_f32_e32 v20, v78, v18
	v_pk_mul_f32 v[20:21], v[18:19], v[20:21] op_sel:[1,0]
	v_pk_mul_f32 v[16:17], v[18:19], v[16:17] op_sel:[1,0]
	v_pk_fma_f32 v[18:19], v[206:207], v[20:21], v[210:211]
	v_pk_fma_f32 v[16:17], v[204:205], v[16:17], v[208:209]
	v_cndmask_b32_e32 v19, v147, v19, vcc
	v_cndmask_b32_e32 v18, v147, v18, vcc
	v_cndmask_b32_e32 v17, v147, v17, vcc
	v_cndmask_b32_e32 v16, v147, v16, vcc
	v_lshl_add_u64 v[20:21], v[128:129], 2, s[0:1]
	global_store_dwordx4 v[20:21], v[16:19], off nt
	v_lshl_add_u64 v[20:21], v[128:129], 1, s[4:5]
	v_add_u32_e32 v128, 0x48080, v60
	v_cvt_pk_bf16_f32 v16, v16, v17
	v_cvt_pk_bf16_f32 v17, v18, v19
	ds_read_b64 v[18:19], v139 offset:9344
	global_store_dwordx2 v[20:21], v[16:17], off
	s_waitcnt lgkmcnt(0)
	v_sub_f32_e32 v17, v73, v18
	v_sub_f32_e32 v16, v72, v18
	v_sub_f32_e32 v21, v75, v18
	v_sub_f32_e32 v20, v74, v18
	v_pk_mul_f32 v[20:21], v[18:19], v[20:21] op_sel:[1,0]
	v_pk_mul_f32 v[16:17], v[18:19], v[16:17] op_sel:[1,0]
	v_pk_fma_f32 v[18:19], v[206:207], v[20:21], v[210:211]
	v_pk_fma_f32 v[16:17], v[204:205], v[16:17], v[208:209]
	v_cndmask_b32_e32 v19, v147, v19, vcc
	v_cndmask_b32_e32 v18, v147, v18, vcc
	v_cndmask_b32_e32 v17, v147, v17, vcc
	v_cndmask_b32_e32 v16, v147, v16, vcc
	v_lshl_add_u64 v[20:21], v[128:129], 2, s[0:1]
	global_store_dwordx4 v[20:21], v[16:19], off nt
	v_lshl_add_u64 v[20:21], v[128:129], 1, s[4:5]
	v_add_u32_e32 v128, 0x50080, v60
	v_cvt_pk_bf16_f32 v16, v16, v17
	v_cvt_pk_bf16_f32 v17, v18, v19
	ds_read_b64 v[18:19], v139 offset:9472
	global_store_dwordx2 v[20:21], v[16:17], off
	s_waitcnt lgkmcnt(0)
	v_sub_f32_e32 v17, v69, v18
	v_sub_f32_e32 v16, v68, v18
	v_sub_f32_e32 v21, v71, v18
	v_sub_f32_e32 v20, v70, v18
	v_pk_mul_f32 v[20:21], v[18:19], v[20:21] op_sel:[1,0]
	v_pk_mul_f32 v[16:17], v[18:19], v[16:17] op_sel:[1,0]
	v_pk_fma_f32 v[18:19], v[206:207], v[20:21], v[210:211]
	v_pk_fma_f32 v[16:17], v[204:205], v[16:17], v[208:209]
	v_cndmask_b32_e32 v19, v147, v19, vcc
	v_cndmask_b32_e32 v18, v147, v18, vcc
	v_cndmask_b32_e32 v17, v147, v17, vcc
	v_cndmask_b32_e32 v16, v147, v16, vcc
	v_lshl_add_u64 v[20:21], v[128:129], 2, s[0:1]
	global_store_dwordx4 v[20:21], v[16:19], off nt
	v_lshl_add_u64 v[20:21], v[128:129], 1, s[4:5]
	v_add_u32_e32 v128, 0x58080, v60
	v_cvt_pk_bf16_f32 v16, v16, v17
	v_cvt_pk_bf16_f32 v17, v18, v19
	ds_read_b64 v[18:19], v139 offset:9600
	global_store_dwordx2 v[20:21], v[16:17], off
	s_waitcnt lgkmcnt(0)
	v_sub_f32_e32 v17, v65, v18
	v_sub_f32_e32 v16, v64, v18
	v_sub_f32_e32 v21, v67, v18
	v_sub_f32_e32 v20, v66, v18
	v_pk_mul_f32 v[20:21], v[18:19], v[20:21] op_sel:[1,0]
	v_pk_mul_f32 v[16:17], v[18:19], v[16:17] op_sel:[1,0]
	v_pk_fma_f32 v[18:19], v[206:207], v[20:21], v[210:211]
	v_pk_fma_f32 v[16:17], v[204:205], v[16:17], v[208:209]
	v_cndmask_b32_e32 v19, v147, v19, vcc
	v_cndmask_b32_e32 v18, v147, v18, vcc
	v_cndmask_b32_e32 v17, v147, v17, vcc
	v_cndmask_b32_e32 v16, v147, v16, vcc
	v_lshl_add_u64 v[20:21], v[128:129], 2, s[0:1]
	global_store_dwordx4 v[20:21], v[16:19], off nt
	s_nop 1
	v_cvt_pk_bf16_f32 v16, v16, v17
	v_cvt_pk_bf16_f32 v17, v18, v19
	v_lshl_add_u64 v[18:19], v[128:129], 1, s[4:5]
	global_store_dwordx2 v[18:19], v[16:17], off
	ds_read_b64 v[24:25], v139 offset:8192
	v_lshl_add_u32 v28, v146, 11, v138
	v_add_u32_e32 v128, 0x90, v28
	v_lshl_add_u64 v[26:27], v[128:129], 2, s[0:1]
	s_waitcnt lgkmcnt(0)
	v_sub_f32_e32 v13, v13, v24
	v_sub_f32_e32 v12, v12, v24
	v_sub_f32_e32 v15, v15, v24
	v_sub_f32_e32 v14, v14, v24
	v_pk_mul_f32 v[14:15], v[24:25], v[14:15] op_sel:[1,0]
	v_pk_mul_f32 v[12:13], v[24:25], v[12:13] op_sel:[1,0]
	v_lshl_add_u64 v[24:25], v[128:129], 1, s[4:5]
	v_add_u32_e32 v128, 0x8090, v28
	v_pk_fma_f32 v[12:13], v[212:213], v[12:13], v[160:161]
	v_pk_fma_f32 v[14:15], v[214:215], v[14:15], v[162:163]
	v_cndmask_b32_e32 v13, v147, v13, vcc
	v_cndmask_b32_e32 v15, v147, v15, vcc
	v_cndmask_b32_e32 v14, v147, v14, vcc
	v_cndmask_b32_e32 v12, v147, v12, vcc
	global_store_dwordx4 v[26:27], v[12:15], off nt
	s_nop 1
	v_cvt_pk_bf16_f32 v12, v12, v13
	v_cvt_pk_bf16_f32 v13, v14, v15
	ds_read_b64 v[14:15], v139 offset:8320
	global_store_dwordx2 v[24:25], v[12:13], off
	v_lshl_add_u64 v[12:13], v[128:129], 2, s[0:1]
	s_waitcnt lgkmcnt(0)
	v_sub_f32_e32 v9, v9, v14
	v_sub_f32_e32 v8, v8, v14
	v_sub_f32_e32 v11, v11, v14
	v_sub_f32_e32 v10, v10, v14
	v_pk_mul_f32 v[10:11], v[14:15], v[10:11] op_sel:[1,0]
	v_pk_mul_f32 v[8:9], v[14:15], v[8:9] op_sel:[1,0]
	v_pk_fma_f32 v[10:11], v[214:215], v[10:11], v[162:163]
	v_pk_fma_f32 v[8:9], v[212:213], v[8:9], v[160:161]
	v_cndmask_b32_e32 v11, v147, v11, vcc
	v_cndmask_b32_e32 v10, v147, v10, vcc
	v_cndmask_b32_e32 v9, v147, v9, vcc
	v_cndmask_b32_e32 v8, v147, v8, vcc
	global_store_dwordx4 v[12:13], v[8:11], off nt
	v_lshl_add_u64 v[12:13], v[128:129], 1, s[4:5]
	v_add_u32_e32 v128, 0x10090, v28
	v_cvt_pk_bf16_f32 v8, v8, v9
	v_cvt_pk_bf16_f32 v9, v10, v11
	ds_read_b64 v[10:11], v139 offset:8448
	global_store_dwordx2 v[12:13], v[8:9], off
	v_lshl_add_u64 v[8:9], v[128:129], 2, s[0:1]
	s_waitcnt lgkmcnt(0)
	v_sub_f32_e32 v5, v5, v10
	v_sub_f32_e32 v4, v4, v10
	v_sub_f32_e32 v7, v7, v10
	v_sub_f32_e32 v6, v6, v10
	v_pk_mul_f32 v[6:7], v[10:11], v[6:7] op_sel:[1,0]
	v_pk_mul_f32 v[4:5], v[10:11], v[4:5] op_sel:[1,0]
	v_pk_fma_f32 v[6:7], v[214:215], v[6:7], v[162:163]
	v_pk_fma_f32 v[4:5], v[212:213], v[4:5], v[160:161]
	v_cndmask_b32_e32 v7, v147, v7, vcc
	v_cndmask_b32_e32 v6, v147, v6, vcc
	v_cndmask_b32_e32 v5, v147, v5, vcc
	v_cndmask_b32_e32 v4, v147, v4, vcc
	global_store_dwordx4 v[8:9], v[4:7], off nt
	v_lshl_add_u64 v[8:9], v[128:129], 1, s[4:5]
	v_add_u32_e32 v128, 0x18090, v28
	v_cvt_pk_bf16_f32 v4, v4, v5
	v_cvt_pk_bf16_f32 v5, v6, v7
	ds_read_b64 v[6:7], v139 offset:8576
	global_store_dwordx2 v[8:9], v[4:5], off
	v_lshl_add_u64 v[4:5], v[128:129], 2, s[0:1]
	s_waitcnt lgkmcnt(0)
	v_sub_f32_e32 v1, v1, v6
	v_sub_f32_e32 v0, v0, v6
	v_sub_f32_e32 v3, v3, v6
	v_sub_f32_e32 v2, v2, v6
	v_pk_mul_f32 v[2:3], v[6:7], v[2:3] op_sel:[1,0]
	v_pk_mul_f32 v[0:1], v[6:7], v[0:1] op_sel:[1,0]
	v_pk_fma_f32 v[2:3], v[214:215], v[2:3], v[162:163]
	v_pk_fma_f32 v[0:1], v[212:213], v[0:1], v[160:161]
	v_cndmask_b32_e32 v3, v147, v3, vcc
	v_cndmask_b32_e32 v2, v147, v2, vcc
	v_cndmask_b32_e32 v1, v147, v1, vcc
	v_cndmask_b32_e32 v0, v147, v0, vcc
	global_store_dwordx4 v[4:5], v[0:3], off nt
	v_lshl_add_u64 v[4:5], v[128:129], 1, s[4:5]
	v_add_u32_e32 v128, 0x40090, v28
	v_cvt_pk_bf16_f32 v0, v0, v1
	v_cvt_pk_bf16_f32 v1, v2, v3
	ds_read_b64 v[2:3], v139 offset:9216
	global_store_dwordx2 v[4:5], v[0:1], off
	s_waitcnt lgkmcnt(0)
	v_sub_f32_e32 v1, v45, v2
	v_sub_f32_e32 v0, v44, v2
	v_sub_f32_e32 v5, v47, v2
	v_sub_f32_e32 v4, v46, v2
	v_pk_mul_f32 v[4:5], v[2:3], v[4:5] op_sel:[1,0]
	v_pk_mul_f32 v[0:1], v[2:3], v[0:1] op_sel:[1,0]
	v_pk_fma_f32 v[2:3], v[214:215], v[4:5], v[162:163]
	v_pk_fma_f32 v[0:1], v[212:213], v[0:1], v[160:161]
	v_cndmask_b32_e32 v3, v147, v3, vcc
	v_cndmask_b32_e32 v2, v147, v2, vcc
	v_cndmask_b32_e32 v1, v147, v1, vcc
	v_cndmask_b32_e32 v0, v147, v0, vcc
	v_lshl_add_u64 v[4:5], v[128:129], 2, s[0:1]
	global_store_dwordx4 v[4:5], v[0:3], off nt
	v_lshl_add_u64 v[4:5], v[128:129], 1, s[4:5]
	v_add_u32_e32 v128, 0x48090, v28
	v_cvt_pk_bf16_f32 v0, v0, v1
	v_cvt_pk_bf16_f32 v1, v2, v3
	ds_read_b64 v[2:3], v139 offset:9344
	global_store_dwordx2 v[4:5], v[0:1], off
	s_waitcnt lgkmcnt(0)
	v_sub_f32_e32 v1, v41, v2
	v_sub_f32_e32 v0, v40, v2
	v_sub_f32_e32 v5, v43, v2
	v_sub_f32_e32 v4, v42, v2
	v_pk_mul_f32 v[4:5], v[2:3], v[4:5] op_sel:[1,0]
	v_pk_mul_f32 v[0:1], v[2:3], v[0:1] op_sel:[1,0]
	v_pk_fma_f32 v[2:3], v[214:215], v[4:5], v[162:163]
	v_pk_fma_f32 v[0:1], v[212:213], v[0:1], v[160:161]
	v_cndmask_b32_e32 v3, v147, v3, vcc
	v_cndmask_b32_e32 v2, v147, v2, vcc
	v_cndmask_b32_e32 v1, v147, v1, vcc
	v_cndmask_b32_e32 v0, v147, v0, vcc
	v_lshl_add_u64 v[4:5], v[128:129], 2, s[0:1]
	global_store_dwordx4 v[4:5], v[0:3], off nt
	v_lshl_add_u64 v[4:5], v[128:129], 1, s[4:5]
	v_add_u32_e32 v128, 0x50090, v28
	v_cvt_pk_bf16_f32 v0, v0, v1
	v_cvt_pk_bf16_f32 v1, v2, v3
	ds_read_b64 v[2:3], v139 offset:9472
	global_store_dwordx2 v[4:5], v[0:1], off
	s_waitcnt lgkmcnt(0)
	v_sub_f32_e32 v1, v37, v2
	v_sub_f32_e32 v0, v36, v2
	v_sub_f32_e32 v5, v39, v2
	v_sub_f32_e32 v4, v38, v2
	v_pk_mul_f32 v[4:5], v[2:3], v[4:5] op_sel:[1,0]
	v_pk_mul_f32 v[0:1], v[2:3], v[0:1] op_sel:[1,0]
	v_pk_fma_f32 v[2:3], v[214:215], v[4:5], v[162:163]
	v_pk_fma_f32 v[0:1], v[212:213], v[0:1], v[160:161]
	v_cndmask_b32_e32 v3, v147, v3, vcc
	v_cndmask_b32_e32 v2, v147, v2, vcc
	v_cndmask_b32_e32 v1, v147, v1, vcc
	v_cndmask_b32_e32 v0, v147, v0, vcc
	v_lshl_add_u64 v[4:5], v[128:129], 2, s[0:1]
	global_store_dwordx4 v[4:5], v[0:3], off nt
	v_lshl_add_u64 v[4:5], v[128:129], 1, s[4:5]
	v_add_u32_e32 v128, 0x58090, v28
	v_cvt_pk_bf16_f32 v0, v0, v1
	v_cvt_pk_bf16_f32 v1, v2, v3
	ds_read_b64 v[2:3], v139 offset:9600
	global_store_dwordx2 v[4:5], v[0:1], off
	s_waitcnt lgkmcnt(0)
	v_sub_f32_e32 v1, v33, v2
	v_sub_f32_e32 v0, v32, v2
	v_sub_f32_e32 v5, v35, v2
	v_sub_f32_e32 v4, v34, v2
	v_pk_mul_f32 v[4:5], v[2:3], v[4:5] op_sel:[1,0]
	v_pk_mul_f32 v[0:1], v[2:3], v[0:1] op_sel:[1,0]
	v_pk_fma_f32 v[2:3], v[214:215], v[4:5], v[162:163]
	v_pk_fma_f32 v[0:1], v[212:213], v[0:1], v[160:161]
	v_cndmask_b32_e32 v3, v147, v3, vcc
	v_cndmask_b32_e32 v2, v147, v2, vcc
	v_cndmask_b32_e32 v1, v147, v1, vcc
	v_cndmask_b32_e32 v0, v147, v0, vcc
	v_lshl_add_u64 v[4:5], v[128:129], 2, s[0:1]
	global_store_dwordx4 v[4:5], v[0:3], off nt
	s_nop 1
	v_cvt_pk_bf16_f32 v0, v0, v1
	v_cvt_pk_bf16_f32 v1, v2, v3
	v_lshl_add_u64 v[2:3], v[128:129], 1, s[4:5]
	global_store_dwordx2 v[2:3], v[0:1], off
